# adaLN GEMV partials: weight stream software-pipelined (two 8-row batches in flight, batch 0 before the silu prologue)
# baseline (speedup 1.0000x reference)
.LBB0_46:
	s_mul_hi_i32 s0, s11, 0x2aaaaaab
	s_ashr_i32 s1, s0, 3
	s_lshr_b32 s4, s0, 31
	s_add_i32 s1, s1, s4
	s_ashr_i32 s5, s1, 31
	s_lshr_b32 s5, s5, 27
	s_add_i32 s5, s1, s5
	s_andn2_b32 s5, s5, 31
	s_sub_i32 s12, s1, s5
	s_lshl_b32 s5, s12, 6
	v_add_u32_e32 v0, s5, v20
	v_ashrrev_i32_e32 v1, 31, v0
	v_lshlrev_b64 v[2:3], 2, v[0:1]
	v_readlane_b32 s16, v239, 3
	v_add_u32_e32 v0, 0x800, v0
	v_readlane_b32 s18, v239, 5
	v_readlane_b32 s19, v239, 6
	v_ashrrev_i32_e32 v1, 31, v0
	v_readlane_b32 s22, v239, 9
	v_readlane_b32 s23, v239, 10
	v_lshl_add_u64 v[4:5], s[18:19], 0, v[2:3]
	v_lshl_add_u64 v[0:1], v[0:1], 2, s[18:19]
	global_load_dword v4, v[4:5], off
	s_nop 0
	global_load_dword v5, v[0:1], off
	v_lshl_add_u64 v[0:1], s[22:23], 0, v[2:3]
	global_load_dword v1, v[0:1], off
	s_ashr_i32 s13, s0, 8
	s_mul_i32 s1, s1, 48
	s_add_i32 s13, s13, s4
	s_sub_i32 s1, s11, s1
	s_mul_i32 s4, s13, 0x6000000
	v_lshl_add_u32 v16, s1, 8, v21
	s_mul_i32 s1, s12, 0x300000
	s_mul_hi_i32 s0, s13, 0x6000000
	s_mul_hi_i32 s5, s5, 0xc000
	s_add_u32 s1, s4, s1
	s_addc_u32 s0, s0, s5
	s_add_u32 s6, s2, s1
	s_addc_u32 s7, s3, s0
	v_mov_b32_e32 v0, 0
	v_ashrrev_i32_e32 v17, 31, v16
	s_mov_b32 s98, 0xfffd0000
	s_mov_b32 s99, -1
	s_mov_b32 s100, 0xc000
	s_mov_b32 s101, 0
	v_lshl_add_u64 v[224:225], v[16:17], 2, s[6:7]
	v_lshl_add_u64 v[224:225], v[224:225], 0, s[98:99]
	global_load_dwordx4 v[160:163], v[224:225], off
	v_lshl_add_u64 v[224:225], v[224:225], 0, s[100:101]
	global_load_dwordx4 v[164:167], v[224:225], off
	v_lshl_add_u64 v[224:225], v[224:225], 0, s[100:101]
	global_load_dwordx4 v[168:171], v[224:225], off
	v_lshl_add_u64 v[224:225], v[224:225], 0, s[100:101]
	global_load_dwordx4 v[172:175], v[224:225], off
	v_lshl_add_u64 v[224:225], v[224:225], 0, s[100:101]
	global_load_dwordx4 v[176:179], v[224:225], off
	v_lshl_add_u64 v[224:225], v[224:225], 0, s[100:101]
	global_load_dwordx4 v[180:183], v[224:225], off
	v_lshl_add_u64 v[224:225], v[224:225], 0, s[100:101]
	global_load_dwordx4 v[184:187], v[224:225], off
	v_lshl_add_u64 v[224:225], v[224:225], 0, s[100:101]
	global_load_dwordx4 v[188:191], v[224:225], off
	v_lshl_add_u64 v[224:225], v[224:225], 0, s[100:101]
	v_readlane_b32 s17, v239, 4
	v_readlane_b32 s20, v239, 7
	v_readlane_b32 s21, v239, 8
	v_readlane_b32 s24, v239, 11
	v_readlane_b32 s25, v239, 12
	v_readlane_b32 s26, v239, 13
	v_readlane_b32 s27, v239, 14
	v_readlane_b32 s28, v239, 15
	v_readlane_b32 s29, v239, 16
	v_readlane_b32 s30, v239, 17
	v_readlane_b32 s31, v239, 18
	s_waitcnt vmcnt(10)
	v_mul_f32_e32 v2, 0xbfb8aa3b, v4
	s_waitcnt vmcnt(9)
	v_mul_f32_e32 v3, 0xbfb8aa3b, v5
	v_fma_f32 v7, v4, s8, -v2
	v_rndne_f32_e32 v8, v2
	s_waitcnt vmcnt(8)
	v_mul_f32_e32 v6, 0xbfb8aa3b, v1
	v_fma_f32 v9, v5, s8, -v3
	v_rndne_f32_e32 v10, v3
	v_fmac_f32_e32 v7, 0xb2a5705f, v4
	v_sub_f32_e32 v2, v2, v8
	v_fma_f32 v11, v1, s8, -v6
	v_rndne_f32_e32 v12, v6
	v_fmac_f32_e32 v9, 0xb2a5705f, v5
	v_sub_f32_e32 v3, v3, v10
	v_add_f32_e32 v2, v2, v7
	v_cvt_i32_f32_e32 v8, v8
	v_fmac_f32_e32 v11, 0xb2a5705f, v1
	v_sub_f32_e32 v6, v6, v12
	v_add_f32_e32 v3, v3, v9
	v_exp_f32_e32 v2, v2
	v_cvt_i32_f32_e32 v10, v10
	v_add_f32_e32 v6, v6, v11
	v_exp_f32_e32 v3, v3
	v_cvt_i32_f32_e32 v12, v12
	v_exp_f32_e32 v6, v6
	v_ldexp_f32 v2, v2, v8
	v_cmp_nlt_f32_e32 vcc, s9, v4
	v_ldexp_f32 v3, v3, v10
	v_ldexp_f32 v6, v6, v12
	v_cndmask_b32_e32 v2, 0, v2, vcc
	v_cmp_nlt_f32_e32 vcc, s9, v5
	s_nop 1
	v_cndmask_b32_e32 v3, 0, v3, vcc
	v_cmp_nlt_f32_e32 vcc, s9, v1
	s_nop 1
	v_cndmask_b32_e32 v6, 0, v6, vcc
	v_cmp_ngt_f32_e32 vcc, s10, v4
	s_nop 1
	v_cndmask_b32_e32 v2, v22, v2, vcc
	v_cmp_ngt_f32_e32 vcc, s10, v5
	v_add_f32_e32 v2, 1.0, v2
	v_div_scale_f32 v7, s[0:1], v2, v2, v4
	v_cndmask_b32_e32 v3, v22, v3, vcc
	v_cmp_ngt_f32_e32 vcc, s10, v1
	v_add_f32_e32 v3, 1.0, v3
	v_div_scale_f32 v9, s[0:1], v3, v3, v5
	v_cndmask_b32_e32 v6, v22, v6, vcc
	v_add_f32_e32 v6, 1.0, v6
	v_rcp_f32_e32 v12, v7
	v_div_scale_f32 v11, s[4:5], v6, v6, v1
	v_rcp_f32_e32 v13, v9
	v_rcp_f32_e32 v14, v11
	v_fma_f32 v18, -v7, v12, 1.0
	v_div_scale_f32 v8, vcc, v4, v2, v4
	v_fma_f32 v19, -v9, v13, 1.0
	v_fmac_f32_e32 v12, v18, v12
	v_div_scale_f32 v10, s[0:1], v5, v3, v5
	v_fma_f32 v23, -v11, v14, 1.0
	v_fmac_f32_e32 v13, v19, v13
	v_mul_f32_e32 v18, v8, v12
	v_div_scale_f32 v15, s[4:5], v1, v6, v1
	v_fmac_f32_e32 v14, v23, v14
	v_mul_f32_e32 v19, v10, v13
	v_fma_f32 v23, -v7, v18, v8
	v_mul_f32_e32 v25, v15, v14
	v_fma_f32 v24, -v9, v19, v10
	v_fmac_f32_e32 v18, v23, v12
	v_fma_f32 v26, -v11, v25, v15
	v_fmac_f32_e32 v19, v24, v13
	v_fma_f32 v7, -v7, v18, v8
	v_fmac_f32_e32 v25, v26, v14
	v_fma_f32 v8, -v9, v19, v10
	v_div_fmas_f32 v7, v7, v12, v18
	s_mov_b64 vcc, s[0:1]
	v_fma_f32 v9, -v11, v25, v15
	v_div_fixup_f32 v23, v7, v2, v4
	v_div_fmas_f32 v2, v8, v13, v19
	s_mov_b64 vcc, s[4:5]
	v_div_fixup_f32 v24, v2, v3, v5
	v_div_fmas_f32 v2, v9, v14, v25
	v_div_fixup_f32 v25, v2, v6, v1
	v_lshl_add_u64 v[18:19], v[16:17], 2, s[6:7]
	s_mov_b32 s5, 0
	v_mov_b32_e32 v1, v0
	v_mov_b32_e32 v2, v0
	v_mov_b32_e32 v3, v0
	v_mov_b32_e32 v8, v0
	v_mov_b32_e32 v9, v0
	v_mov_b32_e32 v10, v0
	v_mov_b32_e32 v11, v0
	v_mov_b32_e32 v4, v0
	v_mov_b32_e32 v5, v0
	v_mov_b32_e32 v6, v0
	v_mov_b32_e32 v7, v0
.LBB0_47:
	global_load_dwordx4 v[192:195], v[224:225], off
	v_lshl_add_u64 v[224:225], v[224:225], 0, s[100:101]
	global_load_dwordx4 v[196:199], v[224:225], off
	v_lshl_add_u64 v[224:225], v[224:225], 0, s[100:101]
	global_load_dwordx4 v[200:203], v[224:225], off
	v_lshl_add_u64 v[224:225], v[224:225], 0, s[100:101]
	global_load_dwordx4 v[204:207], v[224:225], off
	v_lshl_add_u64 v[224:225], v[224:225], 0, s[100:101]
	global_load_dwordx4 v[208:211], v[224:225], off
	v_lshl_add_u64 v[224:225], v[224:225], 0, s[100:101]
	global_load_dwordx4 v[212:215], v[224:225], off
	v_lshl_add_u64 v[224:225], v[224:225], 0, s[100:101]
	global_load_dwordx4 v[216:219], v[224:225], off
	v_lshl_add_u64 v[224:225], v[224:225], 0, s[100:101]
	global_load_dwordx4 v[220:223], v[224:225], off
	v_lshl_add_u64 v[224:225], v[224:225], 0, s[100:101]
	s_add_i32 s1, s5, 1
	s_add_i32 s7, s5, 2
	s_add_i32 s15, s5, 3
	s_add_i32 s18, s5, 4
	s_add_i32 s19, s5, 5
	s_add_i32 s21, s5, 6
	s_add_i32 s23, s5, 7
	s_nop 3
	v_readlane_b32 s4, v23, s5
	v_readlane_b32 s6, v24, s5
	v_readlane_b32 s0, v25, s5
	v_readlane_b32 s14, v23, s1
	v_readlane_b32 s20, v24, s1
	v_readlane_b32 s22, v25, s1
	v_readlane_b32 s24, v23, s7
	v_readlane_b32 s26, v24, s7
	v_readlane_b32 s28, v25, s7
	v_readlane_b32 s30, v23, s15
	v_readlane_b32 s34, v24, s15
	v_readlane_b32 s36, v25, s15
	v_readlane_b32 s38, v23, s18
	v_readlane_b32 s40, v24, s18
	v_readlane_b32 s42, v25, s18
	v_readlane_b32 s60, v23, s19
	v_readlane_b32 s62, v24, s19
	v_readlane_b32 s64, v25, s19
	v_readlane_b32 s66, v23, s21
	v_readlane_b32 s68, v24, s21
	v_readlane_b32 s70, v25, s21
	v_readlane_b32 s72, v23, s23
	v_readlane_b32 s74, v24, s23
	v_readlane_b32 s18, v25, s23
	s_waitcnt vmcnt(15)
	v_pk_fma_f32 v[2:3], v[162:163], s[4:5], v[2:3] op_sel_hi:[1,0,1]
	v_pk_fma_f32 v[0:1], v[160:161], s[4:5], v[0:1] op_sel_hi:[1,0,1]
	v_pk_fma_f32 v[10:11], v[162:163], s[6:7], v[10:11] op_sel_hi:[1,0,1]
	v_pk_fma_f32 v[8:9], v[160:161], s[6:7], v[8:9] op_sel_hi:[1,0,1]
	v_pk_fma_f32 v[6:7], v[162:163], s[0:1], v[6:7] op_sel_hi:[1,0,1]
	v_pk_fma_f32 v[4:5], v[160:161], s[0:1], v[4:5] op_sel_hi:[1,0,1]
	s_waitcnt vmcnt(14)
	v_pk_fma_f32 v[2:3], v[166:167], s[14:15], v[2:3] op_sel_hi:[1,0,1]
	v_pk_fma_f32 v[0:1], v[164:165], s[14:15], v[0:1] op_sel_hi:[1,0,1]
	v_pk_fma_f32 v[10:11], v[166:167], s[20:21], v[10:11] op_sel_hi:[1,0,1]
	v_pk_fma_f32 v[8:9], v[164:165], s[20:21], v[8:9] op_sel_hi:[1,0,1]
	v_pk_fma_f32 v[6:7], v[166:167], s[22:23], v[6:7] op_sel_hi:[1,0,1]
	v_pk_fma_f32 v[4:5], v[164:165], s[22:23], v[4:5] op_sel_hi:[1,0,1]
	s_waitcnt vmcnt(13)
	v_pk_fma_f32 v[2:3], v[170:171], s[24:25], v[2:3] op_sel_hi:[1,0,1]
	v_pk_fma_f32 v[0:1], v[168:169], s[24:25], v[0:1] op_sel_hi:[1,0,1]
	v_pk_fma_f32 v[10:11], v[170:171], s[26:27], v[10:11] op_sel_hi:[1,0,1]
	v_pk_fma_f32 v[8:9], v[168:169], s[26:27], v[8:9] op_sel_hi:[1,0,1]
	v_pk_fma_f32 v[6:7], v[170:171], s[28:29], v[6:7] op_sel_hi:[1,0,1]
	v_pk_fma_f32 v[4:5], v[168:169], s[28:29], v[4:5] op_sel_hi:[1,0,1]
	s_waitcnt vmcnt(12)
	v_pk_fma_f32 v[2:3], v[174:175], s[30:31], v[2:3] op_sel_hi:[1,0,1]
	v_pk_fma_f32 v[0:1], v[172:173], s[30:31], v[0:1] op_sel_hi:[1,0,1]
	v_pk_fma_f32 v[10:11], v[174:175], s[34:35], v[10:11] op_sel_hi:[1,0,1]
	v_pk_fma_f32 v[8:9], v[172:173], s[34:35], v[8:9] op_sel_hi:[1,0,1]
	v_pk_fma_f32 v[6:7], v[174:175], s[36:37], v[6:7] op_sel_hi:[1,0,1]
	v_pk_fma_f32 v[4:5], v[172:173], s[36:37], v[4:5] op_sel_hi:[1,0,1]
	s_waitcnt vmcnt(11)
	v_pk_fma_f32 v[2:3], v[178:179], s[38:39], v[2:3] op_sel_hi:[1,0,1]
	v_pk_fma_f32 v[0:1], v[176:177], s[38:39], v[0:1] op_sel_hi:[1,0,1]
	v_pk_fma_f32 v[10:11], v[178:179], s[40:41], v[10:11] op_sel_hi:[1,0,1]
	v_pk_fma_f32 v[8:9], v[176:177], s[40:41], v[8:9] op_sel_hi:[1,0,1]
	v_pk_fma_f32 v[6:7], v[178:179], s[42:43], v[6:7] op_sel_hi:[1,0,1]
	v_pk_fma_f32 v[4:5], v[176:177], s[42:43], v[4:5] op_sel_hi:[1,0,1]
	s_waitcnt vmcnt(10)
	v_pk_fma_f32 v[2:3], v[182:183], s[60:61], v[2:3] op_sel_hi:[1,0,1]
	v_pk_fma_f32 v[0:1], v[180:181], s[60:61], v[0:1] op_sel_hi:[1,0,1]
	v_pk_fma_f32 v[10:11], v[182:183], s[62:63], v[10:11] op_sel_hi:[1,0,1]
	v_pk_fma_f32 v[8:9], v[180:181], s[62:63], v[8:9] op_sel_hi:[1,0,1]
	v_pk_fma_f32 v[6:7], v[182:183], s[64:65], v[6:7] op_sel_hi:[1,0,1]
	v_pk_fma_f32 v[4:5], v[180:181], s[64:65], v[4:5] op_sel_hi:[1,0,1]
	s_waitcnt vmcnt(9)
	v_pk_fma_f32 v[2:3], v[186:187], s[66:67], v[2:3] op_sel_hi:[1,0,1]
	v_pk_fma_f32 v[0:1], v[184:185], s[66:67], v[0:1] op_sel_hi:[1,0,1]
	v_pk_fma_f32 v[10:11], v[186:187], s[68:69], v[10:11] op_sel_hi:[1,0,1]
	v_pk_fma_f32 v[8:9], v[184:185], s[68:69], v[8:9] op_sel_hi:[1,0,1]
	v_pk_fma_f32 v[6:7], v[186:187], s[70:71], v[6:7] op_sel_hi:[1,0,1]
	v_pk_fma_f32 v[4:5], v[184:185], s[70:71], v[4:5] op_sel_hi:[1,0,1]
	s_waitcnt vmcnt(8)
	v_pk_fma_f32 v[2:3], v[190:191], s[72:73], v[2:3] op_sel_hi:[1,0,1]
	v_pk_fma_f32 v[0:1], v[188:189], s[72:73], v[0:1] op_sel_hi:[1,0,1]
	v_pk_fma_f32 v[10:11], v[190:191], s[74:75], v[10:11] op_sel_hi:[1,0,1]
	v_pk_fma_f32 v[8:9], v[188:189], s[74:75], v[8:9] op_sel_hi:[1,0,1]
	v_pk_fma_f32 v[6:7], v[190:191], s[18:19], v[6:7] op_sel_hi:[1,0,1]
	v_pk_fma_f32 v[4:5], v[188:189], s[18:19], v[4:5] op_sel_hi:[1,0,1]
	s_add_i32 s5, s5, 8
	s_cmp_eq_u32 s5, 56
	s_cbranch_scc1 .Lmodp_tail
	global_load_dwordx4 v[160:163], v[224:225], off
	v_lshl_add_u64 v[224:225], v[224:225], 0, s[100:101]
	global_load_dwordx4 v[164:167], v[224:225], off
	v_lshl_add_u64 v[224:225], v[224:225], 0, s[100:101]
	global_load_dwordx4 v[168:171], v[224:225], off
	v_lshl_add_u64 v[224:225], v[224:225], 0, s[100:101]
	global_load_dwordx4 v[172:175], v[224:225], off
	v_lshl_add_u64 v[224:225], v[224:225], 0, s[100:101]
	global_load_dwordx4 v[176:179], v[224:225], off
	v_lshl_add_u64 v[224:225], v[224:225], 0, s[100:101]
	global_load_dwordx4 v[180:183], v[224:225], off
	v_lshl_add_u64 v[224:225], v[224:225], 0, s[100:101]
	global_load_dwordx4 v[184:187], v[224:225], off
	v_lshl_add_u64 v[224:225], v[224:225], 0, s[100:101]
	global_load_dwordx4 v[188:191], v[224:225], off
	v_lshl_add_u64 v[224:225], v[224:225], 0, s[100:101]
	s_add_i32 s1, s5, 1
	s_add_i32 s7, s5, 2
	s_add_i32 s15, s5, 3
	s_add_i32 s18, s5, 4
	s_add_i32 s19, s5, 5
	s_add_i32 s21, s5, 6
	s_add_i32 s23, s5, 7
	s_nop 3
	v_readlane_b32 s4, v23, s5
	v_readlane_b32 s6, v24, s5
	v_readlane_b32 s0, v25, s5
	v_readlane_b32 s14, v23, s1
	v_readlane_b32 s20, v24, s1
	v_readlane_b32 s22, v25, s1
	v_readlane_b32 s24, v23, s7
	v_readlane_b32 s26, v24, s7
	v_readlane_b32 s28, v25, s7
	v_readlane_b32 s30, v23, s15
	v_readlane_b32 s34, v24, s15
	v_readlane_b32 s36, v25, s15
	v_readlane_b32 s38, v23, s18
	v_readlane_b32 s40, v24, s18
	v_readlane_b32 s42, v25, s18
	v_readlane_b32 s60, v23, s19
	v_readlane_b32 s62, v24, s19
	v_readlane_b32 s64, v25, s19
	v_readlane_b32 s66, v23, s21
	v_readlane_b32 s68, v24, s21
	v_readlane_b32 s70, v25, s21
	v_readlane_b32 s72, v23, s23
	v_readlane_b32 s74, v24, s23
	v_readlane_b32 s18, v25, s23
	s_waitcnt vmcnt(15)
	v_pk_fma_f32 v[2:3], v[194:195], s[4:5], v[2:3] op_sel_hi:[1,0,1]
	v_pk_fma_f32 v[0:1], v[192:193], s[4:5], v[0:1] op_sel_hi:[1,0,1]
	v_pk_fma_f32 v[10:11], v[194:195], s[6:7], v[10:11] op_sel_hi:[1,0,1]
	v_pk_fma_f32 v[8:9], v[192:193], s[6:7], v[8:9] op_sel_hi:[1,0,1]
	v_pk_fma_f32 v[6:7], v[194:195], s[0:1], v[6:7] op_sel_hi:[1,0,1]
	v_pk_fma_f32 v[4:5], v[192:193], s[0:1], v[4:5] op_sel_hi:[1,0,1]
	s_waitcnt vmcnt(14)
	v_pk_fma_f32 v[2:3], v[198:199], s[14:15], v[2:3] op_sel_hi:[1,0,1]
	v_pk_fma_f32 v[0:1], v[196:197], s[14:15], v[0:1] op_sel_hi:[1,0,1]
	v_pk_fma_f32 v[10:11], v[198:199], s[20:21], v[10:11] op_sel_hi:[1,0,1]
	v_pk_fma_f32 v[8:9], v[196:197], s[20:21], v[8:9] op_sel_hi:[1,0,1]
	v_pk_fma_f32 v[6:7], v[198:199], s[22:23], v[6:7] op_sel_hi:[1,0,1]
	v_pk_fma_f32 v[4:5], v[196:197], s[22:23], v[4:5] op_sel_hi:[1,0,1]
	s_waitcnt vmcnt(13)
	v_pk_fma_f32 v[2:3], v[202:203], s[24:25], v[2:3] op_sel_hi:[1,0,1]
	v_pk_fma_f32 v[0:1], v[200:201], s[24:25], v[0:1] op_sel_hi:[1,0,1]
	v_pk_fma_f32 v[10:11], v[202:203], s[26:27], v[10:11] op_sel_hi:[1,0,1]
	v_pk_fma_f32 v[8:9], v[200:201], s[26:27], v[8:9] op_sel_hi:[1,0,1]
	v_pk_fma_f32 v[6:7], v[202:203], s[28:29], v[6:7] op_sel_hi:[1,0,1]
	v_pk_fma_f32 v[4:5], v[200:201], s[28:29], v[4:5] op_sel_hi:[1,0,1]
	s_waitcnt vmcnt(12)
	v_pk_fma_f32 v[2:3], v[206:207], s[30:31], v[2:3] op_sel_hi:[1,0,1]
	v_pk_fma_f32 v[0:1], v[204:205], s[30:31], v[0:1] op_sel_hi:[1,0,1]
	v_pk_fma_f32 v[10:11], v[206:207], s[34:35], v[10:11] op_sel_hi:[1,0,1]
	v_pk_fma_f32 v[8:9], v[204:205], s[34:35], v[8:9] op_sel_hi:[1,0,1]
	v_pk_fma_f32 v[6:7], v[206:207], s[36:37], v[6:7] op_sel_hi:[1,0,1]
	v_pk_fma_f32 v[4:5], v[204:205], s[36:37], v[4:5] op_sel_hi:[1,0,1]
	s_waitcnt vmcnt(11)
	v_pk_fma_f32 v[2:3], v[210:211], s[38:39], v[2:3] op_sel_hi:[1,0,1]
	v_pk_fma_f32 v[0:1], v[208:209], s[38:39], v[0:1] op_sel_hi:[1,0,1]
	v_pk_fma_f32 v[10:11], v[210:211], s[40:41], v[10:11] op_sel_hi:[1,0,1]
	v_pk_fma_f32 v[8:9], v[208:209], s[40:41], v[8:9] op_sel_hi:[1,0,1]
	v_pk_fma_f32 v[6:7], v[210:211], s[42:43], v[6:7] op_sel_hi:[1,0,1]
	v_pk_fma_f32 v[4:5], v[208:209], s[42:43], v[4:5] op_sel_hi:[1,0,1]
	s_waitcnt vmcnt(10)
	v_pk_fma_f32 v[2:3], v[214:215], s[60:61], v[2:3] op_sel_hi:[1,0,1]
	v_pk_fma_f32 v[0:1], v[212:213], s[60:61], v[0:1] op_sel_hi:[1,0,1]
	v_pk_fma_f32 v[10:11], v[214:215], s[62:63], v[10:11] op_sel_hi:[1,0,1]
	v_pk_fma_f32 v[8:9], v[212:213], s[62:63], v[8:9] op_sel_hi:[1,0,1]
	v_pk_fma_f32 v[6:7], v[214:215], s[64:65], v[6:7] op_sel_hi:[1,0,1]
	v_pk_fma_f32 v[4:5], v[212:213], s[64:65], v[4:5] op_sel_hi:[1,0,1]
	s_waitcnt vmcnt(9)
	v_pk_fma_f32 v[2:3], v[218:219], s[66:67], v[2:3] op_sel_hi:[1,0,1]
	v_pk_fma_f32 v[0:1], v[216:217], s[66:67], v[0:1] op_sel_hi:[1,0,1]
	v_pk_fma_f32 v[10:11], v[218:219], s[68:69], v[10:11] op_sel_hi:[1,0,1]
	v_pk_fma_f32 v[8:9], v[216:217], s[68:69], v[8:9] op_sel_hi:[1,0,1]
	v_pk_fma_f32 v[6:7], v[218:219], s[70:71], v[6:7] op_sel_hi:[1,0,1]
	v_pk_fma_f32 v[4:5], v[216:217], s[70:71], v[4:5] op_sel_hi:[1,0,1]
	s_waitcnt vmcnt(8)
	v_pk_fma_f32 v[2:3], v[222:223], s[72:73], v[2:3] op_sel_hi:[1,0,1]
	v_pk_fma_f32 v[0:1], v[220:221], s[72:73], v[0:1] op_sel_hi:[1,0,1]
	v_pk_fma_f32 v[10:11], v[222:223], s[74:75], v[10:11] op_sel_hi:[1,0,1]
	v_pk_fma_f32 v[8:9], v[220:221], s[74:75], v[8:9] op_sel_hi:[1,0,1]
	v_pk_fma_f32 v[6:7], v[222:223], s[18:19], v[6:7] op_sel_hi:[1,0,1]
	v_pk_fma_f32 v[4:5], v[220:221], s[18:19], v[4:5] op_sel_hi:[1,0,1]
	s_add_i32 s5, s5, 8
	s_branch .LBB0_47
.Lmodp_tail:
	s_add_i32 s1, s5, 1
	s_add_i32 s7, s5, 2
	s_add_i32 s15, s5, 3
	s_add_i32 s18, s5, 4
	s_add_i32 s19, s5, 5
	s_add_i32 s21, s5, 6
	s_add_i32 s23, s5, 7
	s_nop 3
	v_readlane_b32 s4, v23, s5
	v_readlane_b32 s6, v24, s5
	v_readlane_b32 s0, v25, s5
	v_readlane_b32 s14, v23, s1
	v_readlane_b32 s20, v24, s1
	v_readlane_b32 s22, v25, s1
	v_readlane_b32 s24, v23, s7
	v_readlane_b32 s26, v24, s7
	v_readlane_b32 s28, v25, s7
	v_readlane_b32 s30, v23, s15
	v_readlane_b32 s34, v24, s15
	v_readlane_b32 s36, v25, s15
	v_readlane_b32 s38, v23, s18
	v_readlane_b32 s40, v24, s18
	v_readlane_b32 s42, v25, s18
	v_readlane_b32 s60, v23, s19
	v_readlane_b32 s62, v24, s19
	v_readlane_b32 s64, v25, s19
	v_readlane_b32 s66, v23, s21
	v_readlane_b32 s68, v24, s21
	v_readlane_b32 s70, v25, s21
	v_readlane_b32 s72, v23, s23
	v_readlane_b32 s74, v24, s23
	v_readlane_b32 s18, v25, s23
	s_waitcnt vmcnt(7)
	v_pk_fma_f32 v[2:3], v[194:195], s[4:5], v[2:3] op_sel_hi:[1,0,1]
	v_pk_fma_f32 v[0:1], v[192:193], s[4:5], v[0:1] op_sel_hi:[1,0,1]
	v_pk_fma_f32 v[10:11], v[194:195], s[6:7], v[10:11] op_sel_hi:[1,0,1]
	v_pk_fma_f32 v[8:9], v[192:193], s[6:7], v[8:9] op_sel_hi:[1,0,1]
	v_pk_fma_f32 v[6:7], v[194:195], s[0:1], v[6:7] op_sel_hi:[1,0,1]
	v_pk_fma_f32 v[4:5], v[192:193], s[0:1], v[4:5] op_sel_hi:[1,0,1]
	s_waitcnt vmcnt(6)
	v_pk_fma_f32 v[2:3], v[198:199], s[14:15], v[2:3] op_sel_hi:[1,0,1]
	v_pk_fma_f32 v[0:1], v[196:197], s[14:15], v[0:1] op_sel_hi:[1,0,1]
	v_pk_fma_f32 v[10:11], v[198:199], s[20:21], v[10:11] op_sel_hi:[1,0,1]
	v_pk_fma_f32 v[8:9], v[196:197], s[20:21], v[8:9] op_sel_hi:[1,0,1]
	v_pk_fma_f32 v[6:7], v[198:199], s[22:23], v[6:7] op_sel_hi:[1,0,1]
	v_pk_fma_f32 v[4:5], v[196:197], s[22:23], v[4:5] op_sel_hi:[1,0,1]
	s_waitcnt vmcnt(5)
	v_pk_fma_f32 v[2:3], v[202:203], s[24:25], v[2:3] op_sel_hi:[1,0,1]
	v_pk_fma_f32 v[0:1], v[200:201], s[24:25], v[0:1] op_sel_hi:[1,0,1]
	v_pk_fma_f32 v[10:11], v[202:203], s[26:27], v[10:11] op_sel_hi:[1,0,1]
	v_pk_fma_f32 v[8:9], v[200:201], s[26:27], v[8:9] op_sel_hi:[1,0,1]
	v_pk_fma_f32 v[6:7], v[202:203], s[28:29], v[6:7] op_sel_hi:[1,0,1]
	v_pk_fma_f32 v[4:5], v[200:201], s[28:29], v[4:5] op_sel_hi:[1,0,1]
	s_waitcnt vmcnt(4)
	v_pk_fma_f32 v[2:3], v[206:207], s[30:31], v[2:3] op_sel_hi:[1,0,1]
	v_pk_fma_f32 v[0:1], v[204:205], s[30:31], v[0:1] op_sel_hi:[1,0,1]
	v_pk_fma_f32 v[10:11], v[206:207], s[34:35], v[10:11] op_sel_hi:[1,0,1]
	v_pk_fma_f32 v[8:9], v[204:205], s[34:35], v[8:9] op_sel_hi:[1,0,1]
	v_pk_fma_f32 v[6:7], v[206:207], s[36:37], v[6:7] op_sel_hi:[1,0,1]
	v_pk_fma_f32 v[4:5], v[204:205], s[36:37], v[4:5] op_sel_hi:[1,0,1]
	s_waitcnt vmcnt(3)
	v_pk_fma_f32 v[2:3], v[210:211], s[38:39], v[2:3] op_sel_hi:[1,0,1]
	v_pk_fma_f32 v[0:1], v[208:209], s[38:39], v[0:1] op_sel_hi:[1,0,1]
	v_pk_fma_f32 v[10:11], v[210:211], s[40:41], v[10:11] op_sel_hi:[1,0,1]
	v_pk_fma_f32 v[8:9], v[208:209], s[40:41], v[8:9] op_sel_hi:[1,0,1]
	v_pk_fma_f32 v[6:7], v[210:211], s[42:43], v[6:7] op_sel_hi:[1,0,1]
	v_pk_fma_f32 v[4:5], v[208:209], s[42:43], v[4:5] op_sel_hi:[1,0,1]
	s_waitcnt vmcnt(2)
	v_pk_fma_f32 v[2:3], v[214:215], s[60:61], v[2:3] op_sel_hi:[1,0,1]
	v_pk_fma_f32 v[0:1], v[212:213], s[60:61], v[0:1] op_sel_hi:[1,0,1]
	v_pk_fma_f32 v[10:11], v[214:215], s[62:63], v[10:11] op_sel_hi:[1,0,1]
	v_pk_fma_f32 v[8:9], v[212:213], s[62:63], v[8:9] op_sel_hi:[1,0,1]
	v_pk_fma_f32 v[6:7], v[214:215], s[64:65], v[6:7] op_sel_hi:[1,0,1]
	v_pk_fma_f32 v[4:5], v[212:213], s[64:65], v[4:5] op_sel_hi:[1,0,1]
	s_waitcnt vmcnt(1)
	v_pk_fma_f32 v[2:3], v[218:219], s[66:67], v[2:3] op_sel_hi:[1,0,1]
	v_pk_fma_f32 v[0:1], v[216:217], s[66:67], v[0:1] op_sel_hi:[1,0,1]
	v_pk_fma_f32 v[10:11], v[218:219], s[68:69], v[10:11] op_sel_hi:[1,0,1]
	v_pk_fma_f32 v[8:9], v[216:217], s[68:69], v[8:9] op_sel_hi:[1,0,1]
	v_pk_fma_f32 v[6:7], v[218:219], s[70:71], v[6:7] op_sel_hi:[1,0,1]
	v_pk_fma_f32 v[4:5], v[216:217], s[70:71], v[4:5] op_sel_hi:[1,0,1]
	s_waitcnt vmcnt(0)
	v_pk_fma_f32 v[2:3], v[222:223], s[72:73], v[2:3] op_sel_hi:[1,0,1]
	v_pk_fma_f32 v[0:1], v[220:221], s[72:73], v[0:1] op_sel_hi:[1,0,1]
	v_pk_fma_f32 v[10:11], v[222:223], s[74:75], v[10:11] op_sel_hi:[1,0,1]
	v_pk_fma_f32 v[8:9], v[220:221], s[74:75], v[8:9] op_sel_hi:[1,0,1]
	v_pk_fma_f32 v[6:7], v[222:223], s[18:19], v[6:7] op_sel_hi:[1,0,1]
	v_pk_fma_f32 v[4:5], v[220:221], s[18:19], v[4:5] op_sel_hi:[1,0,1]
	s_lshl_b32 s0, s12, 2
	s_add_i32 s0, s0, s13
	v_readlane_b32 s52, v240, 22
	s_mul_i32 s1, s0, 3
	s_mul_i32 s0, s0, 0x24000
	v_readlane_b32 s54, v240, 24
	s_mul_hi_i32 s1, s1, 0xc000
	v_readlane_b32 s55, v240, 25
	s_add_u32 s0, s54, s0
	s_addc_u32 s1, s55, s1
	v_lshl_add_u64 v[12:13], v[16:17], 2, s[0:1]
	global_store_dwordx4 v[12:13], v[0:3], off
	v_readlane_b32 s0, v238, 3
	s_add_i32 s11, s11, s0
	v_add_co_u32_e32 v0, vcc, 0xc000, v12
	v_readlane_b32 s53, v240, 23
	s_nop 0
	v_addc_co_u32_e32 v1, vcc, 0, v13, vcc
	global_store_dwordx4 v[0:1], v[8:11], off
	v_add_co_u32_e32 v0, vcc, 0x18000, v12
	v_readlane_b32 s56, v240, 26
	v_readlane_b32 s57, v240, 27
	v_readlane_b32 s60, v240, 30
	v_readlane_b32 s61, v240, 31
	v_readlane_b32 s62, v240, 32
	v_readlane_b32 s63, v240, 33
	v_readlane_b32 s66, v240, 36
	v_readlane_b32 s67, v240, 37
	v_addc_co_u32_e32 v1, vcc, 0, v13, vcc
	s_cmpk_gt_i32 s11, 0x17ff
	v_readlane_b32 s58, v240, 28
	v_readlane_b32 s59, v240, 29
	v_readlane_b32 s64, v240, 34
	v_readlane_b32 s65, v240, 35
	v_readlane_b32 s1, v238, 4
	global_store_dwordx4 v[0:1], v[4:7], off
	s_cbranch_scc0 .LBB0_46
